# SA-item-setup-loads-issued-together-single-wait
# baseline (speedup 1.0000x reference)
; #define GAS __attribute__((address_space(1)))
; #define LAS __attribute__((address_space(3)))
; template <int MODE> __device__ __forceinline__ void item(const void* const* in, const bf16* QABS, const unsigned char* W8, const bf16* ROPEB, float* PO, float* PL, float sref, int b, int half, LAS unsigned char* lds, int tid_, int wave, int lane_) {
;     ...
;     for (int e = tid; e < 36 * 32; e += 512) *(LAS v4u*)(lds + OFF_QA + e * 16) = *(const GAS v4u*)(QABS + ((size_t)b * 36 * 32 + e) * 8);
;     if (tid < NPAGES / 2) *(LAS int*)(lds + OFF_PHYS + tid * 4) = page_table[b * NPAGES + half * (NPAGES / 2) + tid];
;     v8i wf[4][2];
; #pragma unroll
;     for (int s = 0; s < 4; ++s)
; #pragma unroll
;         for (int nb = 0; nb < 2; ++nb) { const GAS v4u* wp = (const GAS v4u*)(W8 + (size_t)(wave * QKN + 32 * nb + r32) * KVL + 64 * s + 32 * hi); const v4u a = wp[0], bq = wp[1];
;             wf[s][nb] = (v8i){(int)a.x, (int)a.y, (int)a.z, (int)a.w, (int)bq.x, (int)bq.y, (int)bq.z, (int)bq.w}; }
;     if (tid < 32) *(LAS float*)(lds + OFF_GK + tid * 4) = g_k[64 + tid];
;     asm volatile("s_waitcnt vmcnt(0) lgkmcnt(0)" ::: "memory");
; #pragma unroll
;     for (int s = 0; s < 4; ++s) asm volatile("" : "+v"(wf[s][0]), "+v"(wf[s][1]));
;     __builtin_amdgcn_s_barrier(); asm volatile("" ::: "memory");
.LBB0_1346:
	v_mov_b32_e32 v188, v196
	s_movk_i32 s2, 0x480
	s_ashr_i32 s1, s64, 1
	s_nop 0
	v_cmp_gt_i32_e32 vcc, s2, v188
	v_ashrrev_i32_e32 v189, 31, v188
	s_and_saveexec_b64 s[2:3], vcc
	s_cbranch_execz .LBB0_1349
	s_mul_i32 s4, s1, 0x4800
	v_readlane_b32 s6, v255, 19
	s_mul_hi_i32 s5, s1, 0x4800
	s_add_u32 s4, s6, s4
	v_readlane_b32 s6, v255, 21
	s_addc_u32 s5, s6, s5
	v_add_u32_e32 v4, 0xfffffe00, v188
	v_lshl_add_u32 v5, v188, 4, s97
	v_lshl_add_u64 v[2:3], v[188:189], 4, s[4:5]
	s_mov_b64 s[4:5], 0
	s_mov_b64 s[98:99], 0x2000
	global_load_dwordx4 v[204:207], v[2:3], off
	v_lshl_add_u64 v[2:3], v[2:3], 0, s[98:99]
	v_mov_b32_e32 v218, v5
	global_load_dwordx4 v[208:211], v[2:3], off
	v_lshl_add_u64 v[2:3], v[2:3], 0, s[98:99]
	v_cmp_gt_i32_e32 vcc, 0x80, v188
	s_mov_b64 s[4:5], exec
	s_and_saveexec_b64 s[100:101], vcc
	global_load_dwordx4 v[212:215], v[2:3], off
	s_mov_b64 exec, s[100:101]
	s_mov_b64 s[6:7], 0x2000
	s_movk_i32 s6, 0x27f
.LBB0_1349:
	s_or_b64 exec, exec, s[2:3]
	s_and_b32 s16, s64, 1
	v_cmp_gt_i32_e32 vcc, 32, v188
	v_lshl_add_u32 v2, v188, 2, 0
	s_and_saveexec_b64 s[2:3], vcc
	s_cbranch_execz .LBB0_1351
	s_lshl_b32 s4, s16, 5
	s_lshl_b32 s1, s1, 6
	s_or_b32 s1, s4, s1
	v_add_u32_e32 v4, s1, v188
	v_readlane_b32 s40, v254, 15
	v_ashrrev_i32_e32 v5, 31, v4
	v_readlane_b32 s52, v254, 27
	v_readlane_b32 s53, v254, 28
	v_readlane_b32 s41, v254, 16
	v_readlane_b32 s42, v254, 17
	v_lshl_add_u64 v[4:5], v[4:5], 2, s[52:53]
	global_load_dword v216, v[4:5], off
	v_add_u32_e32 v4, 0x20c80, v2
	v_readlane_b32 s43, v254, 18
	v_readlane_b32 s44, v254, 19
	v_readlane_b32 s45, v254, 20
	v_readlane_b32 s46, v254, 21
	v_readlane_b32 s47, v254, 22
	v_readlane_b32 s48, v254, 23
	v_readlane_b32 s49, v254, 24
	v_readlane_b32 s50, v254, 25
	v_readlane_b32 s51, v254, 26
	v_readlane_b32 s54, v254, 29
	v_readlane_b32 s55, v254, 30
.LBB0_1351:
	s_or_b64 exec, exec, s[2:3]
	v_and_b32_e32 v201, 31, v188
	v_or_b32_e32 v4, s34, v201
	v_ashrrev_i32_e32 v5, 31, v4
	v_bfe_u32 v202, v188, 5, 1
	v_lshlrev_b64 v[8:9], 8, v[4:5]
	v_or_b32_e32 v4, 32, v4
	v_lshlrev_b32_e32 v186, 5, v202
	v_ashrrev_i32_e32 v5, 31, v4
	v_lshl_add_u64 v[6:7], s[12:13], 0, v[186:187]
	v_lshlrev_b64 v[4:5], 8, v[4:5]
	v_lshl_add_u64 v[8:9], v[6:7], 0, v[8:9]
	v_lshl_add_u64 v[4:5], v[6:7], 0, v[4:5]
	global_load_dwordx4 v[70:73], v[8:9], off offset:16
	global_load_dwordx4 v[66:69], v[8:9], off
	global_load_dwordx4 v[78:81], v[4:5], off offset:16
	global_load_dwordx4 v[74:77], v[4:5], off
	global_load_dwordx4 v[86:89], v[8:9], off offset:80
	global_load_dwordx4 v[82:85], v[8:9], off offset:64
	global_load_dwordx4 v[94:97], v[4:5], off offset:80
	global_load_dwordx4 v[90:93], v[4:5], off offset:64
	global_load_dwordx4 v[102:105], v[8:9], off offset:144
	global_load_dwordx4 v[98:101], v[8:9], off offset:128
	global_load_dwordx4 v[110:113], v[4:5], off offset:144
	global_load_dwordx4 v[106:109], v[4:5], off offset:128
	global_load_dwordx4 v[118:121], v[8:9], off offset:208
	global_load_dwordx4 v[114:117], v[8:9], off offset:192
	global_load_dwordx4 v[126:129], v[4:5], off offset:208
	global_load_dwordx4 v[122:125], v[4:5], off offset:192
	s_and_saveexec_b64 s[2:3], vcc
	s_cbranch_execz .LBB0_1353
	v_readlane_b32 s40, v254, 47
	v_readlane_b32 s44, v254, 51
	v_readlane_b32 s45, v254, 52
	v_add_u32_e32 v2, 0x20d00, v2
	v_readlane_b32 s41, v254, 48
	v_lshl_add_u64 v[4:5], v[188:189], 2, s[44:45]
	global_load_dword v217, v[4:5], off offset:256
	v_readlane_b32 s42, v254, 49
	v_readlane_b32 s43, v254, 50
	v_readlane_b32 s46, v254, 53
	v_readlane_b32 s47, v254, 54
	v_readlane_b32 s48, v254, 55
	v_readlane_b32 s49, v254, 56
	v_readlane_b32 s50, v254, 57
	v_readlane_b32 s51, v254, 58
	v_readlane_b32 s52, v254, 59
	v_readlane_b32 s53, v254, 60
	v_readlane_b32 s54, v254, 61
	v_readlane_b32 s55, v254, 62
.LBB0_1353:
	s_or_b64 exec, exec, s[2:3]
	s_add_i32 s1, 0, 0x20c80
	v_mov_b32_e32 v42, v188
	v_mov_b32_e32 v2, s1
	s_waitcnt vmcnt(0) lgkmcnt(0)
	ds_write_b128 v218, v[204:207]
	ds_write_b128 v218, v[208:211] offset:8192
	v_cmp_gt_i32_e32 vcc, 0x80, v188
	s_and_saveexec_b64 s[100:101], vcc
	ds_write_b128 v218, v[212:215] offset:16384
	s_mov_b64 exec, s[100:101]
	v_cmp_gt_i32_e32 vcc, 32, v188
	v_lshl_add_u32 v219, v188, 2, 0
	v_add_u32_e32 v220, 0x20c80, v219
	v_add_u32_e32 v219, 0x20d00, v219
	s_and_saveexec_b64 s[100:101], vcc
	ds_write_b32 v220, v216
	ds_write_b32 v219, v217
	s_mov_b64 exec, s[100:101]
	s_waitcnt lgkmcnt(0)
	s_waitcnt vmcnt(0)
	s_waitcnt vmcnt(8)
	s_waitcnt vmcnt(4)
	s_waitcnt vmcnt(0)
	s_barrier
	ds_read_b32 v2, v2
	v_readlane_b32 s40, v254, 15
	v_and_b32_e32 v44, 63, v42
	v_readlane_b32 s48, v254, 23
	v_readlane_b32 s49, v254, 24
	s_waitcnt lgkmcnt(0)
	v_ashrrev_i32_e32 v3, 31, v2
	v_lshlrev_b64 v[40:41], 7, v[2:3]
	v_lshl_add_u64 v[2:3], v[40:41], 0, s[20:21]
	v_lshlrev_b64 v[2:3], 10, v[2:3]
	v_lshl_add_u64 v[2:3], s[48:49], 0, v[2:3]
	v_lshlrev_b32_e32 v186, 4, v44
	v_lshl_add_u64 v[2:3], v[2:3], 0, v[186:187]
	global_load_dwordx4 v[30:33], v[2:3], off
	v_lshl_add_u64 v[4:5], v[2:3], 0, s[38:39]
	global_load_dwordx4 v[26:29], v[4:5], off
	v_lshl_add_u64 v[4:5], v[2:3], 0, s[68:69]
	global_load_dwordx4 v[22:25], v[4:5], off
	v_lshl_add_u64 v[4:5], v[2:3], 0, s[70:71]
	global_load_dwordx4 v[18:21], v[4:5], off
	v_lshl_add_u64 v[4:5], v[2:3], 0, s[56:57]
	global_load_dwordx4 v[14:17], v[4:5], off
	v_lshl_add_u64 v[4:5], v[2:3], 0, s[58:59]
	global_load_dwordx4 v[10:13], v[4:5], off
	v_lshl_add_u64 v[4:5], v[2:3], 0, s[60:61]
	global_load_dwordx4 v[6:9], v[4:5], off
	v_lshl_add_u64 v[2:3], v[2:3], 0, s[62:63]
	global_load_dwordx4 v[2:5], v[2:3], off
	v_ashrrev_i32_e32 v34, 2, v42
	v_and_b32_e32 v43, 3, v42
	v_readlane_b32 s50, v254, 25
	v_readlane_b32 s51, v254, 26
	s_andn2_b64 vcc, exec, s[28:29]
	v_ashrrev_i32_e32 v35, 31, v34
	v_lshlrev_b32_e32 v38, 4, v43
	v_lshlrev_b32_e32 v36, 3, v43
	v_readlane_b32 s41, v254, 16
	v_readlane_b32 s42, v254, 17
	v_readlane_b32 s43, v254, 18
	v_readlane_b32 s44, v254, 19
	v_readlane_b32 s45, v254, 20
	v_readlane_b32 s46, v254, 21
	v_readlane_b32 s47, v254, 22
	v_readlane_b32 s52, v254, 27
	v_readlane_b32 s53, v254, 28
	v_readlane_b32 s54, v254, 29
	v_readlane_b32 s55, v254, 30
	s_cbranch_vccnz .LBB0_1355
	v_lshl_add_u64 v[40:41], v[40:41], 0, v[34:35]
	v_lshlrev_b64 v[40:41], 7, v[40:41]
	v_lshl_add_u64 v[40:41], s[50:51], 0, v[40:41]
	v_mov_b32_e32 v39, v187
	v_lshl_add_u64 v[40:41], v[40:41], 0, v[38:39]
	global_load_dwordx4 v[146:149], v[40:41], off
	v_lshl_add_u64 v[40:41], v[40:41], 0, 64
	s_lshl_b32 s10, s16, 12
	global_load_dwordx4 v[150:153], v[40:41], off
	v_lshl_add_u64 v[40:41], v[34:35], 0, s[10:11]
	v_lshlrev_b64 v[40:41], 6, v[40:41]
	v_lshl_add_u64 v[40:41], s[14:15], 0, v[40:41]
	v_mov_b32_e32 v37, v187
	v_lshl_add_u64 v[40:41], v[40:41], 0, v[36:37]
	global_load_dwordx2 v[190:191], v[40:41], off
	v_lshl_add_u64 v[40:41], v[40:41], 0, 32
	global_load_dwordx2 v[192:193], v[40:41], off
	s_branch .LBB0_1356

; #define GAS __attribute__((address_space(1)))
; #define LAS __attribute__((address_space(3)))
; template <int MODE> __device__ __forceinline__ void item(const void* const* in, const bf16* QABS, const unsigned char* W8, const bf16* ROPEB, float* PO, float* PL, float sref, int b, int half, LAS unsigned char* lds, int tid_, int wave, int lane_) {
;     ...
;     for (int e = tid; e < 36 * 32; e += 512) *(LAS v4u*)(lds + OFF_QA + e * 16) = *(const GAS v4u*)(QABS + ((size_t)b * 36 * 32 + e) * 8);
;     if (tid < NPAGES / 2) *(LAS int*)(lds + OFF_PHYS + tid * 4) = page_table[b * NPAGES + half * (NPAGES / 2) + tid];
;     v8i wf[4][2];
; #pragma unroll
;     for (int s = 0; s < 4; ++s)
; #pragma unroll
;         for (int nb = 0; nb < 2; ++nb) { const GAS v4u* wp = (const GAS v4u*)(W8 + (size_t)(wave * QKN + 32 * nb + r32) * KVL + 64 * s + 32 * hi); const v4u a = wp[0], bq = wp[1];
;             wf[s][nb] = (v8i){(int)a.x, (int)a.y, (int)a.z, (int)a.w, (int)bq.x, (int)bq.y, (int)bq.z, (int)bq.w}; }
;     if (tid < 32) *(LAS float*)(lds + OFF_GK + tid * 4) = g_k[64 + tid];
;     asm volatile("s_waitcnt vmcnt(0) lgkmcnt(0)" ::: "memory");
; #pragma unroll
;     for (int s = 0; s < 4; ++s) asm volatile("" : "+v"(wf[s][0]), "+v"(wf[s][1]));
;     __builtin_amdgcn_s_barrier(); asm volatile("" ::: "memory");
.LBB0_1448:
	v_mov_b32_e32 v188, v196
	s_movk_i32 s2, 0x480
	s_ashr_i32 s6, s60, 1
	s_nop 0
	v_cmp_gt_i32_e32 vcc, s2, v188
	v_ashrrev_i32_e32 v189, 31, v188
	s_and_saveexec_b64 s[2:3], vcc
	s_cbranch_execz .LBB0_1451
	s_mul_i32 s4, s6, 0x4800
	s_mul_hi_i32 s5, s6, 0x4800
	s_add_u32 s4, s78, s4
	s_addc_u32 s5, s79, s5
	v_add_u32_e32 v4, 0xfffffe00, v188
	v_lshl_add_u32 v5, v188, 4, s92
	v_lshl_add_u64 v[2:3], v[188:189], 4, s[4:5]
	s_mov_b64 s[4:5], 0
	s_mov_b64 s[98:99], 0x2000
	global_load_dwordx4 v[204:207], v[2:3], off
	v_lshl_add_u64 v[2:3], v[2:3], 0, s[98:99]
	v_mov_b32_e32 v218, v5
	global_load_dwordx4 v[208:211], v[2:3], off
	v_lshl_add_u64 v[2:3], v[2:3], 0, s[98:99]
	v_cmp_gt_i32_e32 vcc, 0x80, v188
	s_mov_b64 s[4:5], exec
	s_and_saveexec_b64 s[100:101], vcc
	global_load_dwordx4 v[212:215], v[2:3], off
	s_mov_b64 exec, s[100:101]
	s_movk_i32 s7, 0x27f
	s_mov_b64 s[12:13], 0x2000
.LBB0_1451:
	s_or_b64 exec, exec, s[2:3]
	s_and_b32 s16, s60, 1
	v_cmp_gt_i32_e32 vcc, 32, v188
	v_lshl_add_u32 v2, v188, 2, 0
	s_and_saveexec_b64 s[2:3], vcc
	s_cbranch_execz .LBB0_1453
	s_lshl_b32 s4, s16, 5
	s_lshl_b32 s5, s6, 6
	s_or_b32 s4, s4, s5
	v_add_u32_e32 v4, s4, v188
	v_readlane_b32 s36, v254, 15
	v_ashrrev_i32_e32 v5, 31, v4
	v_readlane_b32 s48, v254, 27
	v_readlane_b32 s49, v254, 28
	v_readlane_b32 s37, v254, 16
	v_readlane_b32 s38, v254, 17
	v_lshl_add_u64 v[4:5], v[4:5], 2, s[48:49]
	global_load_dword v216, v[4:5], off
	v_add_u32_e32 v4, 0x20c80, v2
	v_readlane_b32 s39, v254, 18
	v_readlane_b32 s40, v254, 19
	v_readlane_b32 s41, v254, 20
	v_readlane_b32 s42, v254, 21
	v_readlane_b32 s43, v254, 22
	v_readlane_b32 s44, v254, 23
	v_readlane_b32 s45, v254, 24
	v_readlane_b32 s46, v254, 25
	v_readlane_b32 s47, v254, 26
	v_readlane_b32 s50, v254, 29
	v_readlane_b32 s51, v254, 30
.LBB0_1453:
	s_or_b64 exec, exec, s[2:3]
	v_and_b32_e32 v200, 31, v188
	v_or_b32_e32 v4, s34, v200
	v_ashrrev_i32_e32 v5, 31, v4
	v_bfe_u32 v201, v188, 5, 1
	v_lshlrev_b64 v[8:9], 8, v[4:5]
	v_or_b32_e32 v4, 32, v4
	v_lshlrev_b32_e32 v186, 5, v201
	v_ashrrev_i32_e32 v5, 31, v4
	v_lshl_add_u64 v[6:7], s[8:9], 0, v[186:187]
	v_lshlrev_b64 v[4:5], 8, v[4:5]
	v_lshl_add_u64 v[8:9], v[6:7], 0, v[8:9]
	v_lshl_add_u64 v[4:5], v[6:7], 0, v[4:5]
	global_load_dwordx4 v[70:73], v[8:9], off offset:16
	global_load_dwordx4 v[66:69], v[8:9], off
	global_load_dwordx4 v[78:81], v[4:5], off offset:16
	global_load_dwordx4 v[74:77], v[4:5], off
	global_load_dwordx4 v[86:89], v[8:9], off offset:80
	global_load_dwordx4 v[82:85], v[8:9], off offset:64
	global_load_dwordx4 v[94:97], v[4:5], off offset:80
	global_load_dwordx4 v[90:93], v[4:5], off offset:64
	global_load_dwordx4 v[102:105], v[8:9], off offset:144
	global_load_dwordx4 v[98:101], v[8:9], off offset:128
	global_load_dwordx4 v[110:113], v[4:5], off offset:144
	global_load_dwordx4 v[106:109], v[4:5], off offset:128
	global_load_dwordx4 v[118:121], v[8:9], off offset:208
	global_load_dwordx4 v[114:117], v[8:9], off offset:192
	global_load_dwordx4 v[126:129], v[4:5], off offset:208
	global_load_dwordx4 v[122:125], v[4:5], off offset:192
	s_and_saveexec_b64 s[2:3], vcc
	s_cbranch_execz .LBB0_1455
	v_readlane_b32 s36, v254, 47
	v_readlane_b32 s40, v254, 51
	v_readlane_b32 s41, v254, 52
	v_add_u32_e32 v2, 0x20d00, v2
	v_readlane_b32 s37, v254, 48
	v_lshl_add_u64 v[4:5], v[188:189], 2, s[40:41]
	global_load_dword v217, v[4:5], off offset:256
	v_readlane_b32 s38, v254, 49
	v_readlane_b32 s39, v254, 50
	v_readlane_b32 s42, v254, 53
	v_readlane_b32 s43, v254, 54
	v_readlane_b32 s44, v254, 55
	v_readlane_b32 s45, v254, 56
	v_readlane_b32 s46, v254, 57
	v_readlane_b32 s47, v254, 58
	v_readlane_b32 s48, v254, 59
	v_readlane_b32 s49, v254, 60
	v_readlane_b32 s50, v254, 61
	v_readlane_b32 s51, v254, 62
.LBB0_1455:
	s_or_b64 exec, exec, s[2:3]
	s_add_i32 s2, 0, 0x20c80
	v_mov_b32_e32 v42, v188
	v_mov_b32_e32 v2, s2
	s_waitcnt vmcnt(0) lgkmcnt(0)
	ds_write_b128 v218, v[204:207]
	ds_write_b128 v218, v[208:211] offset:8192
	v_cmp_gt_i32_e32 vcc, 0x80, v188
	s_and_saveexec_b64 s[100:101], vcc
	ds_write_b128 v218, v[212:215] offset:16384
	s_mov_b64 exec, s[100:101]
	v_cmp_gt_i32_e32 vcc, 32, v188
	v_lshl_add_u32 v219, v188, 2, 0
	v_add_u32_e32 v220, 0x20c80, v219
	v_add_u32_e32 v219, 0x20d00, v219
	s_and_saveexec_b64 s[100:101], vcc
	ds_write_b32 v220, v216
	ds_write_b32 v219, v217
	s_mov_b64 exec, s[100:101]
	s_waitcnt lgkmcnt(0)
	s_waitcnt vmcnt(0)
	s_barrier
	ds_read_b32 v2, v2
	v_readlane_b32 s36, v254, 15
	v_and_b32_e32 v44, 63, v42
	v_readlane_b32 s44, v254, 23
	v_readlane_b32 s45, v254, 24
	s_waitcnt lgkmcnt(0)
	v_ashrrev_i32_e32 v3, 31, v2
	v_lshlrev_b64 v[40:41], 7, v[2:3]
	v_lshl_add_u64 v[2:3], v[40:41], 0, s[14:15]
	v_lshlrev_b64 v[2:3], 10, v[2:3]
	v_lshl_add_u64 v[2:3], s[44:45], 0, v[2:3]
	v_lshlrev_b32_e32 v186, 4, v44
	v_lshl_add_u64 v[2:3], v[2:3], 0, v[186:187]
	global_load_dwordx4 v[30:33], v[2:3], off
	v_lshl_add_u64 v[4:5], v[2:3], 0, s[0:1]
	global_load_dwordx4 v[26:29], v[4:5], off
	v_lshl_add_u64 v[4:5], v[2:3], 0, s[68:69]
	global_load_dwordx4 v[22:25], v[4:5], off
	v_lshl_add_u64 v[4:5], v[2:3], 0, s[70:71]
	global_load_dwordx4 v[18:21], v[4:5], off
	v_lshl_add_u64 v[4:5], v[2:3], 0, s[52:53]
	global_load_dwordx4 v[14:17], v[4:5], off
	v_lshl_add_u64 v[4:5], v[2:3], 0, s[54:55]
	global_load_dwordx4 v[10:13], v[4:5], off
	v_lshl_add_u64 v[4:5], v[2:3], 0, s[56:57]
	global_load_dwordx4 v[6:9], v[4:5], off
	v_lshl_add_u64 v[2:3], v[2:3], 0, s[58:59]
	global_load_dwordx4 v[2:5], v[2:3], off
	v_ashrrev_i32_e32 v34, 2, v42
	v_and_b32_e32 v43, 3, v42
	v_readlane_b32 s46, v254, 25
	v_readlane_b32 s47, v254, 26
	s_andn2_b64 vcc, exec, s[18:19]
	v_ashrrev_i32_e32 v35, 31, v34
	v_lshlrev_b32_e32 v38, 4, v43
	v_lshlrev_b32_e32 v36, 3, v43
	v_readlane_b32 s37, v254, 16
	v_readlane_b32 s38, v254, 17
	v_readlane_b32 s39, v254, 18
	v_readlane_b32 s40, v254, 19
	v_readlane_b32 s41, v254, 20
	v_readlane_b32 s42, v254, 21
	v_readlane_b32 s43, v254, 22
	v_readlane_b32 s48, v254, 27
	v_readlane_b32 s49, v254, 28
	v_readlane_b32 s50, v254, 29
	v_readlane_b32 s51, v254, 30
	s_cbranch_vccnz .LBB0_1457
	v_lshl_add_u64 v[40:41], v[40:41], 0, v[34:35]
	v_lshlrev_b64 v[40:41], 7, v[40:41]
	v_lshl_add_u64 v[40:41], s[46:47], 0, v[40:41]
	v_mov_b32_e32 v39, v187
	v_lshl_add_u64 v[40:41], v[40:41], 0, v[38:39]
	global_load_dwordx4 v[146:149], v[40:41], off
	v_lshl_add_u64 v[40:41], v[40:41], 0, 64
	s_lshl_b32 s30, s16, 12
	global_load_dwordx4 v[150:153], v[40:41], off
	v_lshl_add_u64 v[40:41], v[34:35], 0, s[30:31]
	v_lshlrev_b64 v[40:41], 6, v[40:41]
	v_lshl_add_u64 v[40:41], s[10:11], 0, v[40:41]
	v_mov_b32_e32 v37, v187
	v_lshl_add_u64 v[40:41], v[40:41], 0, v[36:37]
	global_load_dwordx2 v[190:191], v[40:41], off
	v_lshl_add_u64 v[40:41], v[40:41], 0, 32
	global_load_dwordx2 v[192:193], v[40:41], off
	s_branch .LBB0_1458
